# attention deferred part: hh0 P*V MFMAs issued right after hh0 pack, interleaved with hh1 exp/sum VALU
# speedup vs baseline: 1.0039x; 1.0039x over previous
; #define LAS __attribute__((address_space(3)))
; DEV unsigned cvt_pk_bf16(float lo, float hi) { unsigned r; asm volatile("v_cvt_pk_bf16_f32 %0, %1, %2" : "=v"(r) : "v"(lo), "v"(hi)); return r; }
; DEV void attn_tile(LAS unsigned char* lds, const bf16x8 (&qf)[2][2], int tl, int kpos0, int mode, bool near, bool rowsel, const float (&cbias)[2],
;                    unsigned kb, unsigned vb_, unsigned btb, int g4, float (&mrun)[2], float (&lrun)[2], f32x4 (&O)[2][4]) {
;     ...
;         float rs = 0.f;
; #pragma unroll
;         for (int kt = 0; kt < 4; ++kt)
; #pragma unroll
;             for (int r = 0; r < 4; ++r) { const float p = __builtin_amdgcn_exp2f(sc[hh][kt][r]); sc[hh][kt][r] = p; rs += p; }
;         lrun[hh] += rs;
; #pragma unroll
;         for (int kc = 0; kc < 2; ++kc) { u32x4 w; w.x = cvt_pk_bf16(sc[hh][2 * kc][0], sc[hh][2 * kc][1]); w.y = cvt_pk_bf16(sc[hh][2 * kc][2], sc[hh][2 * kc][3]);
;             w.z = cvt_pk_bf16(sc[hh][2 * kc + 1][0], sc[hh][2 * kc + 1][1]); w.w = cvt_pk_bf16(sc[hh][2 * kc + 1][2], sc[hh][2 * kc + 1][3]); pf[hh][kc] = as_bf16x8(w); }
;     }
; #pragma unroll
;     for (int dt = 0; dt < 4; ++dt)
; #pragma unroll
;         for (int kc = 0; kc < 2; ++kc) {
;             const u32x2 va = *(const LAS u32x2*)(lds + vb_ + dt * 2304 + kc * 64);
;             const u32x2 vb = *(const LAS u32x2*)(lds + vb_ + dt * 2304 + kc * 64 + 32);
;             const bf16x8 vf = as_bf16x8((u32x4){va.x, va.y, vb.x, vb.y});
; #pragma unroll
;             for (int hh = 0; hh < 2; ++hh) O[hh][dt] = __builtin_amdgcn_mfma_f32_16x16x32_bf16(vf, pf[hh][kc], O[hh][dt], 0, 0, 0);
;         }
; }
.Lst_y_entry:
	v_exp_f32_e32 v92, v92
	v_exp_f32_e32 v93, v93
	v_exp_f32_e32 v94, v94
	v_exp_f32_e32 v95, v95
	v_exp_f32_e32 v88, v88
	v_exp_f32_e32 v89, v89
	v_exp_f32_e32 v90, v90
	v_exp_f32_e32 v91, v91
	v_exp_f32_e32 v153, v84
	v_exp_f32_e32 v154, v85
	v_exp_f32_e32 v155, v86
	v_exp_f32_e32 v156, v87
	v_exp_f32_e32 v157, v80
	v_exp_f32_e32 v158, v81
	v_exp_f32_e32 v159, v82
	v_exp_f32_e32 v160, v83
	v_cvt_pk_bf16_f32 v162, v92, v93
	v_cvt_pk_bf16_f32 v163, v94, v95
	v_cvt_pk_bf16_f32 v164, v88, v89
	v_cvt_pk_bf16_f32 v165, v90, v91
	v_cvt_pk_bf16_f32 v166, v153, v154
	v_cvt_pk_bf16_f32 v167, v155, v156
	v_cvt_pk_bf16_f32 v168, v157, v158
	v_cvt_pk_bf16_f32 v169, v159, v160
	s_waitcnt lgkmcnt(0)
	v_add_f32_e32 v92, 0, v92
	v_add_f32_e32 v92, v93, v92
	v_mfma_f32_16x16x32_bf16 v[44:47], v[232:235], v[162:165], v[44:47]
	v_add_f32_e32 v92, v94, v92
	v_add_f32_e32 v92, v95, v92
	v_add_f32_e32 v88, v88, v92
	v_add_f32_e32 v88, v89, v88
	v_add_f32_e32 v88, v90, v88
	v_add_f32_e32 v88, v91, v88
	v_mfma_f32_16x16x32_bf16 v[56:59], v[240:243], v[162:165], v[56:59]
	v_add_f32_e32 v88, v153, v88
	v_add_f32_e32 v88, v154, v88
	v_add_f32_e32 v88, v155, v88
	v_add_f32_e32 v88, v156, v88
	v_add_f32_e32 v88, v157, v88
	v_exp_f32_e32 v76, v76
	v_mfma_f32_16x16x32_bf16 v[52:55], v[248:251], v[162:165], v[52:55]
	v_add_f32_e32 v88, v158, v88
	v_exp_f32_e32 v77, v77
	v_add_f32_e32 v88, v159, v88
	v_exp_f32_e32 v78, v78
	v_add_f32_e32 v88, v160, v88
	v_exp_f32_e32 v79, v79
	v_mfma_f32_16x16x32_bf16 v[60:63], v[202:205], v[162:165], v[60:63]
	v_add_f32_e32 v151, v151, v88
	v_add_f32_e32 v88, 0, v76
	v_exp_f32_e32 v72, v72
	v_add_f32_e32 v88, v77, v88
	v_exp_f32_e32 v73, v73
	v_add_f32_e32 v88, v78, v88
	v_mfma_f32_16x16x32_bf16 v[44:47], v[236:239], v[166:169], v[44:47]
	v_exp_f32_e32 v74, v74
	v_add_f32_e32 v88, v79, v88
	v_exp_f32_e32 v75, v75
	v_add_f32_e32 v88, v72, v88
	v_exp_f32_e32 v64, v64
	v_add_f32_e32 v88, v73, v88
	v_mfma_f32_16x16x32_bf16 v[56:59], v[244:247], v[166:169], v[56:59]
	v_exp_f32_e32 v65, v65
	v_add_f32_e32 v88, v74, v88
	v_exp_f32_e32 v66, v66
	v_add_f32_e32 v88, v75, v88
	v_exp_f32_e32 v67, v67
	v_add_f32_e32 v88, v64, v88
	v_mfma_f32_16x16x32_bf16 v[52:55], v[198:201], v[166:169], v[52:55]
	v_exp_f32_e32 v89, v68
	v_add_f32_e32 v88, v65, v88
	v_add_f32_e32 v88, v66, v88
	v_add_f32_e32 v88, v67, v88
	v_add_f32_e32 v68, v89, v88
	v_exp_f32_e32 v88, v69
	v_mfma_f32_16x16x32_bf16 v[60:63], v[206:209], v[166:169], v[60:63]
	v_exp_f32_e32 v90, v70
	v_exp_f32_e32 v91, v71
	v_add_f32_e32 v68, v88, v68
	v_add_f32_e32 v68, v90, v68
	v_add_f32_e32 v68, v91, v68
	v_add_f32_e32 v148, v148, v68
	v_cvt_pk_bf16_f32 v68, v76, v77
	v_cvt_pk_bf16_f32 v69, v78, v79
	v_cvt_pk_bf16_f32 v70, v72, v73
	v_cvt_pk_bf16_f32 v71, v74, v75
	v_cvt_pk_bf16_f32 v64, v64, v65
	v_cvt_pk_bf16_f32 v65, v66, v67
	v_cvt_pk_bf16_f32 v66, v89, v88
	v_cvt_pk_bf16_f32 v67, v90, v91
	s_cmp_eq_u32 s100, 1
	s_cbranch_scc0 .Lst_nokpre
	v_add_u32_e32 v228, s98, v141
	ds_read_b128 v[72:75], v228
	ds_read_b128 v[76:79], v228 offset:64
	ds_read_b128 v[80:83], v228 offset:2304
	ds_read_b128 v[84:87], v228 offset:2368
	ds_read_b128 v[88:91], v228 offset:4608
	ds_read_b128 v[154:157], v228 offset:4672
	ds_read_b128 v[92:95], v228 offset:6912
	ds_read_b128 v[158:161], v228 offset:6976
.Lst_nokpre:
	v_mfma_f32_16x16x32_bf16 v[32:35], v[232:235], v[68:71], v[32:35]
	v_mfma_f32_16x16x32_bf16 v[40:43], v[240:243], v[68:71], v[40:43]
	v_mfma_f32_16x16x32_bf16 v[36:39], v[248:251], v[68:71], v[36:39]
	v_mfma_f32_16x16x32_bf16 v[48:51], v[202:205], v[68:71], v[48:51]
	v_mfma_f32_16x16x32_bf16 v[32:35], v[236:239], v[64:67], v[32:35]
	v_mfma_f32_16x16x32_bf16 v[40:43], v[244:247], v[64:67], v[40:43]
	v_mfma_f32_16x16x32_bf16 v[36:39], v[198:201], v[64:67], v[36:39]
	v_mfma_f32_16x16x32_bf16 v[48:51], v[206:209], v[64:67], v[48:51]
	s_bitcmp1_b32 s101, 8
	s_cbranch_scc0 .LBB0_283
	ds_bpermute_b32 v64, v143, v151
	s_and_b32 s6, s101, 0xff
	s_lshl_b32 s6, s6, 1
	v_mov_b32_e32 v66, 0
	s_waitcnt lgkmcnt(0)
	v_add_f32_e32 v64, v151, v64
	ds_bpermute_b32 v65, v144, v64
	s_waitcnt lgkmcnt(0)
	v_add_f32_e32 v65, v64, v65
	v_mov_b32_e32 v64, 0
	v_cmp_lt_f32_e32 vcc, 0, v65
	s_and_saveexec_b64 s[4:5], vcc
	s_cbranch_execz .LBB0_280
	s_cmp_eq_u32 s6, 1
	s_cselect_b64 vcc, -1, 0
	s_cmp_eq_u32 s6, 2
	v_cndmask_b32_e32 v66, v126, v7, vcc
	s_cselect_b64 vcc, -1, 0
	s_cmp_eq_u32 s6, 3
	v_cndmask_b32_e32 v66, v66, v2, vcc
	s_cselect_b64 vcc, -1, 0
	s_cmp_eq_u32 s6, 4
	v_cndmask_b32_e32 v66, v66, v3, vcc
	s_cselect_b64 vcc, -1, 0
	s_cmp_eq_u32 s6, 5
	v_cndmask_b32_e32 v66, v66, v4, vcc
	s_cselect_b64 vcc, -1, 0
	v_cndmask_b32_e32 v66, v66, v5, vcc
	v_div_scale_f32 v67, s[42:43], v65, v65, v66
	v_rcp_f32_e32 v68, v67
	s_nop 0
	v_fma_f32 v69, -v67, v68, 1.0
	v_fmac_f32_e32 v68, v69, v68
	v_div_scale_f32 v69, vcc, v66, v65, v66
	v_mul_f32_e32 v70, v69, v68
	v_fma_f32 v71, -v67, v70, v69
	v_fmac_f32_e32 v70, v71, v68
	v_fma_f32 v67, -v67, v70, v69
	v_div_fmas_f32 v67, v67, v68, v70
	v_div_fixup_f32 v66, v67, v65, v66
